# compression second layer runs on the 192 workgroups idle during the first-layer GEMMs, H1 handed over through a counter instead of a grid barrier
# speedup vs baseline: 1.0118x; 1.0046x over previous
; #define LAS __attribute__((address_space(3)))
; __device__ __forceinline__ void s5_phase(LAS unsigned char* lds, const bf16_t* USSM, const float* S5A, const float* S5B, const float* c_re, const float* c_im, const float* dskip,
;                                          bf16_t* YSSM, int tid, int lane, int wave) {
;     LAS float* carry = (LAS float*)lds;
;     LAS unsigned char* wb = lds + 4096 + wave * 13312;
;     LAS float* BU = (LAS float*)wb;
;     LAS bf16_t* XB = (LAS bf16_t*)(wb + 8448);
;     LAS bf16_t* UST = (LAS bf16_t*)(wb + 8448 + 4352);
;     const int r16 = lane & 15, q4 = lane >> 4;
;     const f32x4 z4 = {0.f, 0.f, 0.f, 0.f};
;     const bf16x8 zf = {0, 0, 0, 0, 0, 0, 0, 0};
;     for (int bg = blockIdx.x; bg < 256; bg += gridDim.x) {
;         const int b = bg >> 6, g = bg & 63;
;         __syncthreads();
;         const float are = S5A[(g * 64 + lane) * 2], aim = S5A[(g * 64 + lane) * 2 + 1];
;         bf16x8 bfr[8], cfr[4];
; #pragma unroll
;         for (int nt = 0; nt < 8; ++nt) { const int pp = nt * 16 + r16, p = pp & 63, im = pp >> 6; bfr[nt] = q4 < 2 ? pack_bf8(S5B + (size_t)(g * 64 + p) * 32 + im * 16 + q4 * 8, 1.f) : zf; }
; #pragma unroll
;         for (int ks = 0; ks < 4; ++ks) { const int pp = ks * 32 + q4 * 8, p = pp & 63, im = pp >> 6; cfr[ks] = pack_bf8((im ? c_im : c_re) + (size_t)(g * 16 + r16) * 64 + p, im ? -1.f : 1.f); }
;         const float dsk = dskip[g * 16 + r16];
;         const bf16_t* ub = USSM + ((size_t)(b * SEQ + wave * 1024)) * 1024 + g * 16;
.LBB0_566:
	s_cmpk_gt_u32 s2, 63
	s_cbranch_scc1 .Lc1sig_done
	s_waitcnt vmcnt(0)
	s_barrier
	v_cmp_eq_u32_e32 vcc, 0, v154
	s_and_saveexec_b64 s[10:11], vcc
	s_cbranch_execz .Lc1sig_skip
	buffer_wbl2 sc1
	s_waitcnt vmcnt(0)
	s_add_u32 s0, s30, 0x38998880
	s_addc_u32 s1, s31, 0
	v_mov_b32_e32 v0, 0
	v_mov_b32_e32 v1, 1
	global_atomic_add v0, v1, s[0:1]
	s_waitcnt vmcnt(0)
.Lc1sig_skip:
	s_or_b64 exec, exec, s[10:11]
.Lc1sig_done:
	s_cmpk_lt_i32 s2, 0x100
	v_readlane_b32 s90, v254, 17
	v_readlane_b32 s92, v254, 15
	s_cselect_b64 s[34:35], -1, 0
	s_cmpk_gt_i32 s2, 0xff
	v_readlane_b32 s91, v254, 18
	v_readlane_b32 s93, v254, 16
	s_cbranch_scc1 .LBB0_598
	s_ashr_i32 s6, s42, 6
	s_mul_i32 s0, s6, 0x3400
	v_and_b32_e32 v106, 63, v154
	s_lshl_b32 s8, s6, 9
	s_add_i32 s10, s0, 0
	v_and_b32_e32 v81, 15, v154
	s_add_i32 s8, s8, 0
	v_lshlrev_b32_e32 v5, 3, v106
	v_bfe_u32 v0, v154, 4, 2
	v_mov_b32_e32 v1, s10
	v_add_u32_e32 v107, s8, v5
	v_add_u32_e32 v108, 0, v5
	v_lshlrev_b32_e32 v5, 5, v81
	v_and_b32_e32 v6, 16, v154
	s_movk_i32 s11, 0x110
	v_lshlrev_b32_e32 v10, 2, v106
	s_lshl_b32 s3, s6, 10
	v_add3_u32 v109, s10, v5, v6
	v_mad_u32_u24 v5, v81, s11, v1
	v_lshl_or_b32 v1, v0, 6, v81
	v_bfe_u32 v8, v154, 2, 4
	v_and_b32_e32 v11, 12, v10
	s_cmp_gt_i32 s6, 0
	v_lshlrev_b32_e32 v9, 6, v8
	v_lshlrev_b32_e32 v12, 2, v11
	v_lshlrev_b32_e32 v112, 1, v1
	v_mov_b32_e32 v83, 0
	v_lshl_add_u32 v3, v81, 2, s10
	s_cselect_b64 s[8:9], -1, 0
	v_add3_u32 v110, s10, v9, v12
	v_lshlrev_b32_e32 v82, 1, v11
	v_readlane_b32 s62, v254, 21
	v_add_u32_e32 v111, s10, v10
	v_add_u32_e32 v113, s10, v112
	v_lshl_add_u32 v114, v1, 2, s10
	s_and_b32 s10, s6, 7
	v_lshl_add_u64 v[84:85], s[22:23], 0, v[82:83]
	v_lshlrev_b32_e32 v82, 5, v0
	v_readlane_b32 s63, v254, 22
	s_cmp_gt_u32 s6, 7
	v_lshlrev_b32_e32 v4, 1, v106
	v_lshl_add_u64 v[86:87], s[62:63], 0, v[82:83]
	s_cselect_b64 s[18:19], -1, 0
	s_and_b32 s11, s6, 0x7ffffff8
	v_lshl_add_u64 v[88:89], s[78:79], 0, v[82:83]
	v_lshl_add_u64 v[90:91], s[80:81], 0, v[82:83]
	v_lshl_or_b32 v82, v81, 11, v6
	v_lshlrev_b32_e32 v80, 3, v0
	v_lshlrev_b32_e32 v2, 6, v81
	v_and_b32_e32 v7, 48, v154
	v_mul_u32_u24_e32 v9, 0x840, v0
	v_sub_u32_e32 v4, 0, v4
	s_cmp_lg_u32 s10, 0
	v_lshl_add_u64 v[0:1], s[30:31], 0, v[82:83]
	s_mov_b64 s[14:15], 0x23900000
	s_mov_b32 s7, 0
	v_cmp_gt_u32_e64 s[0:1], 32, v106
	v_cmp_lt_u32_e64 s[4:5], 31, v106
	v_sub_u32_e32 v115, v114, v112
	s_cselect_b64 s[24:25], -1, 0
	v_lshl_add_u64 v[92:93], v[0:1], 0, s[14:15]
	s_lshl_b32 s27, s2, 7
	s_lshl_b32 s33, s84, 7
	v_or_b32_e32 v116, s3, v8
	s_mov_b64 s[52:53], 0x1000
	s_mov_b64 s[54:55], 0x1040
	v_lshlrev_b32_e32 v117, 2, v2
	s_mov_b64 s[56:57], 0x8000
	v_add_u32_e32 v118, v111, v4
	v_add_u32_e32 v119, v5, v7
	v_mov_b32_e32 v120, 0x800
	v_mov_b32_e32 v121, 0x1800
	v_add_u32_e32 v122, v3, v9
	s_and_b32 s43, s2, 7
	s_lshl_b32 s43, s43, 3
	s_bfe_u32 s42, s2, 0x30003
	s_or_b32 s43, s43, s42
	s_and_b32 s42, s2, 0xc0
	s_or_b32 s43, s43, s42
	s_cmpk_eq_u32 s84, 0x100
	s_cselect_b32 s43, s43, s2
	s_mov_b32 s42, s43
	s_lshl_b32 s27, s43, 7

; __device__ __forceinline__ unsigned xb_ld(unsigned* p)              { return __hip_atomic_load(p, __ATOMIC_RELAXED, __HIP_MEMORY_SCOPE_AGENT); }
; __device__ __forceinline__ unsigned xb_add(unsigned* p, unsigned v) { return __hip_atomic_fetch_add(p, v, __ATOMIC_RELAXED, __HIP_MEMORY_SCOPE_AGENT); }
; #define XB_SPIN(cond, bar) do { unsigned _sp = 0; while (cond) { __builtin_amdgcn_s_sleep(1); \
;     if ((++_sp & 255u) == 0u) { if (xb_ld(&(bar)[XB_TMO])) break; if (_sp > XB_SPIN_CAP) { atomicAdd(&(bar)[XB_TMO], 1u); break; } } } } while (0)
; __device__ __forceinline__ void xcd_barrier(const XcdBarrier& b) {
;     asm volatile("s_waitcnt vmcnt(0)" ::: "memory");
;     __syncthreads();
;     if (threadIdx.x == 0) {
;         unsigned* bar = b.bar;
;         __builtin_amdgcn_s_waitcnt(0);
;         unsigned nloc = b.st[0], nx = b.st[1];
;         if (nloc == 0u) { xcd_barrier_complete(bar, b.x, nloc, nx); b.st[0] = nloc; b.st[1] = nx; }
;         const unsigned old = xb_add(&bar[XB_XSUB(b.x)], 1u);
;         const unsigned gen = old / nloc;
;         if (old + 1u == (gen + 1u) * nloc) {
;             __builtin_amdgcn_fence(__ATOMIC_RELEASE, "agent");
;             asm volatile("s_waitcnt vmcnt(0)" ::: "memory");
;             const unsigned og = xb_add(&bar[XB_TOP], 1u);
;             const unsigned tg = og / nx;
;             if (og + 1u == (tg + 1u) * nx) xb_add(&bar[XB_TOPGEN], 1u);
;             else XB_SPIN(xb_ld(&bar[XB_TOPGEN]) == tg, bar);
.LBB0_598:
	s_barrier
	s_waitcnt vmcnt(0)
	s_barrier
	s_mov_b64 s[0:1], exec
	v_readlane_b32 s4, v254, 3
	v_readlane_b32 s5, v254, 4
	v_readlane_b32 s82, v254, 6
	v_readlane_b32 s78, v254, 13
	s_and_b64 s[4:5], s[0:1], s[4:5]
	v_readlane_b32 s83, v254, 7
	v_readlane_b32 s81, v254, 5
	v_readlane_b32 s79, v254, 14
	s_mov_b64 exec, s[4:5]
	s_branch .LBB0_650
	s_add_i32 s3, 0, 0x20000
	v_mov_b32_e32 v0, s3
	s_waitcnt vmcnt(0) expcnt(0) lgkmcnt(0)
	ds_read_b32 v2, v0
	s_add_i32 s3, 0, 0x20004
	v_mov_b32_e32 v0, s3
	ds_read_b32 v0, v0
	s_waitcnt lgkmcnt(1)
	v_cmp_ne_u32_e32 vcc, 0, v2
	s_cbranch_vccnz .LBB0_614
	s_add_u32 s4, s30, 0x38998a00
	s_addc_u32 s5, s31, 0
	s_add_u32 s6, s30, 0x38998c00
	s_addc_u32 s7, s31, 0
	s_add_u32 s8, s30, 0x38998d00
	s_addc_u32 s9, s31, 0
	s_add_u32 s10, s30, 0x38998e00
	s_addc_u32 s11, s31, 0
	s_add_u32 s12, s30, 0x38998f00
	s_addc_u32 s13, s31, 0
	s_add_u32 s18, s30, 0x38999000
	s_addc_u32 s19, s31, 0
	s_add_u32 s24, s30, 0x38999100
	s_addc_u32 s25, s31, 0
	s_add_u32 s52, s30, 0x38999200
	s_addc_u32 s53, s31, 0
	s_add_u32 s54, s30, 0x38999300
	s_addc_u32 s55, s31, 0
	s_add_u32 s56, s30, 0x38999400
	s_addc_u32 s57, s31, 0
	s_add_u32 s58, s30, 0x38999500
	s_addc_u32 s59, s31, 0
	s_add_u32 s62, s30, 0x38999600
	s_addc_u32 s63, s31, 0
	s_add_u32 s66, s30, 0x38999700
	s_addc_u32 s67, s31, 0
	s_add_u32 s68, s30, 0x38999800
	s_addc_u32 s69, s31, 0
	s_add_u32 s70, s30, 0x38999900
	s_addc_u32 s71, s31, 0
	s_add_u32 s42, s30, 0x38999a00
	v_readlane_b32 s3, v254, 2
	s_addc_u32 s43, s31, 0
	s_mul_i32 s3, s85, s3
	s_add_u32 s14, s30, 0x38999b00
	s_mul_i32 s3, s3, s84
	s_addc_u32 s15, s31, 0
	s_mov_b32 s27, 1
	v_mov_b32_e32 v16, 0
	s_branch .LBB0_602

; __device__ __forceinline__ unsigned f2bf(float f) { unsigned u = __builtin_bit_cast(unsigned, f); return (u + 0x7fffu + ((u >> 16) & 1u)) >> 16; }
; __device__ __forceinline__ void unpack8(u32x4 v, f32x4& a, f32x4& b) { a[0] = bflo(v.x); a[1] = bfhi(v.x); a[2] = bflo(v.y); a[3] = bfhi(v.y); b[0] = bflo(v.z); b[1] = bfhi(v.z); b[2] = bflo(v.w); b[3] = bfhi(v.w); }
; __device__ __forceinline__ void cmp2_phase(LAS unsigned char* lds, const bf16_t* H1K, const bf16_t* H1V, const float* w2k, const float* w2v, bf16_t* KCMP, bf16_t* VCMPT, int tid) {
;     ...
;     for (int i = tid; i < 32768; i += NTHREADS) w2s[i] = i < 16384 ? w2k[i] : w2v[i - 16384];
;     __syncthreads();
;     const int d = tid & 63, rsub = tid >> 6;
;     for (int rg = blockIdx.x; rg < 1024; rg += gridDim.x) {
;         const int row = rg * 8 + rsub; const bf16_t* hk = H1K + (size_t)row * 256; const bf16_t* hv = H1V + (size_t)row * 256;
;         float ak = 0.f, av = 0.f;
;         for (int n = 0; n < 256; n += 8) { f32x4 k0, k1, v0, v1; unpack8(*(const u32x4*)(hk + n), k0, k1); unpack8(*(const u32x4*)(hv + n), v0, v1);
; #pragma unroll
;             for (int j = 0; j < 4; ++j) { ak += k0[j] * w2s[(n + j) * 64 + d] + k1[j] * w2s[(n + 4 + j) * 64 + d]; av += v0[j] * w2s[16384 + (n + j) * 64 + d] + v1[j] * w2s[16384 + (n + 4 + j) * 64 + d]; } }
;         const int bgi = row >> 9, i = row & 511; const bool ok = i < 511;
;         KCMP[(size_t)row * 64 + d] = ok ? (bf16_t)f2bf(ak) : (bf16_t)0;
;         VCMPT[((size_t)(bgi * 64 + d)) * 512 + i] = ok ? (bf16_t)f2bf(av) : (bf16_t)0;
;     }
.LBB0_663:
	s_or_b64 exec, exec, s[12:13]
	s_add_u32 s24, s30, 0x38110000
	v_readlane_b32 s4, v254, 25
	s_addc_u32 s25, s31, 0
	v_readlane_b32 s5, v254, 26
	s_add_u32 s0, s30, 0x38210000
	s_addc_u32 s1, s31, 0
	v_cndmask_b32_e64 v1, 0, 1, s[4:5]
	v_cmp_ne_u32_e64 s[94:95], 1, v1
	s_andn2_b64 vcc, exec, s[4:5]
	s_waitcnt lgkmcnt(0)
	s_barrier
	s_cbranch_vccnz .LBB0_672
	s_cmpk_lt_u32 s2, 64
	s_cbranch_scc1 .LBB0_672
	s_add_u32 s4, s30, 0x38998880
	s_addc_u32 s5, s31, 0
	v_cmp_eq_u32_e32 vcc, 0, v0
	s_and_saveexec_b64 s[8:9], vcc
	s_cbranch_execz .Lc2wait_done
	v_mov_b32_e32 v16, 0
.Lc2wait_spin:
	global_load_dword v17, v16, s[4:5] sc1
	s_waitcnt vmcnt(0)
	v_cmp_gt_u32_e32 vcc, 64, v17
	s_nop 1
	s_cbranch_vccz .Lc2wait_got
	s_sleep 1
	s_branch .Lc2wait_spin
.Lc2wait_got:
	buffer_inv sc1
	s_waitcnt vmcnt(0)
.Lc2wait_done:
	s_or_b64 exec, exec, s[8:9]
	s_barrier
	v_and_b32_e32 v12, 63, v0
	v_ashrrev_i32_e32 v13, 6, v0
	v_lshlrev_b32_e32 v0, 1, v12
	v_mov_b32_e32 v1, 0
	v_readlane_b32 s3, v254, 8
	v_lshl_add_u64 v[2:3], s[24:25], 0, v[0:1]
	v_lshl_add_u32 v14, v12, 2, 0
	s_add_i32 s3, s3, 0xfffffe00
	v_add_u32_e32 v4, s3, v13
	s_mov_b64 s[4:5], 0x400000
	s_mov_b32 s3, 0x400000
	s_movk_i32 s8, 0x1ff
	s_movk_i32 s9, 0x7fff
	s_movk_i32 s10, 0xffc0
	s_add_i32 s11, s2, 0xffffffc0
	s_branch .LBB0_666
.LBB0_665:
	s_or_b64 exec, exec, s[6:7]
	v_ashrrev_i32_e32 v6, 3, v8
	v_and_or_b32 v6, v6, s10, v12
	v_ashrrev_i32_e32 v7, 31, v6
	v_lshlrev_b64 v[6:7], 10, v[6:7]
	v_lshl_add_u64 v[6:7], s[0:1], 0, v[6:7]
	v_lshlrev_b32_e32 v0, 1, v0
	s_add_i32 s11, s11, 0xc0
	v_lshl_add_u64 v[6:7], v[6:7], 0, v[0:1]
	s_cmpk_lt_i32 s11, 0x400
	v_add_u32_e32 v4, 0x600, v4
	global_store_short v[6:7], v5, off
	s_cbranch_scc0 .LBB0_672
